# grid barrier spin loops: s_sleep 4 instead of s_sleep 1 between polls (less polling traffic while stragglers finish)
# baseline (speedup 1.0000x reference)
; __global__ void __launch_bounds__(512) mega_fwd(Params p) {
;     ...
;     asm volatile("s_waitcnt vmcnt(0) lgkmcnt(0)" ::: "memory"); grid.sync();
.LBB0_21:
	s_sleep 4
	global_load_dword v2, v0, s[2:3] offset:32 sc1
	s_waitcnt vmcnt(0)
	v_and_b32_e32 v2, 0xffff0000, v2
	v_cmp_ne_u32_e32 vcc, v2, v1
	s_or_b64 s[4:5], vcc, s[4:5]
	s_andn2_b64 exec, exec, s[4:5]
	s_cbranch_execnz .LBB0_21

; __device__ __forceinline__ unsigned xb_ld(unsigned* p)              { return __hip_atomic_load(p, __ATOMIC_RELAXED, __HIP_MEMORY_SCOPE_AGENT); }
; __device__ __forceinline__ void xcd_barrier_complete(unsigned* bar, unsigned x, unsigned& nloc, unsigned& nx) {
;     ...
;     for (;;) {
;         sum = 0u; cnt = 0u; mine = 0u;
; #pragma unroll
;         for (unsigned j = 0; j < 16; ++j) { const unsigned c = xb_ld(&bar[XB_XCNT(j)]); sum += c; cnt += (c > 0u) ? 1u : 0u; mine = (j == x) ? c : mine; }
;         if (sum == G) break;
;         __builtin_amdgcn_s_sleep(1);
;         if ((++sp & 255u) == 0u) { if (xb_ld(&bar[XB_TMO])) break; if (sp > XB_SPIN_CAP) { atomicAdd(&bar[XB_TMO], 1u); break; } }
;     }
.LBB0_88:
	v_readlane_b32 s8, v251, 45
	v_readlane_b32 s9, v251, 46
	global_load_dword v12, v1, s[18:19] offset:1024 sc1
	global_load_dword v0, v1, s[18:19] offset:1280 sc1
	s_waitcnt lgkmcnt(0)
	global_load_dword v2, v1, s[18:19] offset:1536 sc1
	global_load_dword v3, v1, s[18:19] offset:1792 sc1
	global_load_dword v4, v1, s[18:19] offset:2048 sc1
	global_load_dword v5, v1, s[18:19] offset:2304 sc1
	global_load_dword v6, v1, s[18:19] offset:2560 sc1
	global_load_dword v7, v1, s[18:19] offset:2816 sc1
	global_load_dword v8, v1, s[18:19] offset:3072 sc1
	global_load_dword v9, v1, s[18:19] offset:3328 sc1
	global_load_dword v10, v1, s[18:19] offset:3584 sc1
	global_load_dword v11, v1, s[18:19] offset:3840 sc1
	global_load_dword v13, v1, s[8:9] sc1
	v_readlane_b32 s8, v251, 47
	v_readlane_b32 s9, v251, 48
	s_mov_b64 s[20:21], -1
	s_mov_b64 s[36:37], -1
	s_waitcnt vmcnt(11)
	v_add_u32_e32 v17, v0, v12
	s_nop 0
	global_load_dword v14, v1, s[8:9] sc1
	v_readlane_b32 s8, v251, 49
	v_readlane_b32 s9, v251, 50
	s_waitcnt vmcnt(11)
	v_add_u32_e32 v17, v17, v2
	s_waitcnt vmcnt(10)
	v_add_u32_e32 v17, v17, v3
	s_waitcnt vmcnt(9)
	v_add_u32_e32 v17, v17, v4
	s_waitcnt vmcnt(8)
	v_add_u32_e32 v17, v17, v5
	s_waitcnt vmcnt(7)
	v_add_u32_e32 v17, v17, v6
	global_load_dword v15, v1, s[8:9] sc1
	v_readlane_b32 s8, v251, 51
	v_readlane_b32 s9, v251, 52
	s_waitcnt vmcnt(7)
	v_add_u32_e32 v17, v17, v7
	s_waitcnt vmcnt(6)
	v_add_u32_e32 v17, v17, v8
	s_waitcnt vmcnt(5)
	v_add_u32_e32 v17, v17, v9
	s_waitcnt vmcnt(4)
	v_add_u32_e32 v17, v17, v10
	s_waitcnt vmcnt(3)
	v_add_u32_e32 v17, v17, v11
	global_load_dword v16, v1, s[8:9] sc1
	s_waitcnt vmcnt(3)
	v_add_u32_e32 v17, v17, v13
	v_readlane_b32 s8, v254, 29
	s_waitcnt vmcnt(2)
	v_add_u32_e32 v17, v17, v14
	s_waitcnt vmcnt(1)
	v_add_u32_e32 v17, v17, v15
	s_waitcnt vmcnt(0)
	v_add_u32_e32 v17, v17, v16
	v_cmp_eq_u32_e32 vcc, s8, v17
	s_cbranch_vccnz .LBB0_87
	s_and_b32 s8, s4, 0xff
	s_cmp_eq_u32 s8, 0
	s_mov_b64 s[38:39], -1
	s_sleep 4
	s_cbranch_scc1 .LBB0_92
	s_and_b64 vcc, exec, s[38:39]
	s_cbranch_vccz .LBB0_87

.LBB0_106:
	s_and_b32 s8, s4, 0xff
	s_mov_b64 s[42:43], -1
	s_cmp_lg_u32 s8, 0
	s_mov_b64 s[46:47], -1
	s_sleep 4
	s_cbranch_scc0 .LBB0_109
	s_and_b64 vcc, exec, s[46:47]
	s_cbranch_vccz .LBB0_105

.LBB0_123:
	s_and_b32 s8, s4, 0xff
	s_mov_b64 s[44:45], -1
	s_cmp_lg_u32 s8, 0
	s_mov_b64 s[48:49], -1
	s_sleep 4
	s_cbranch_scc0 .LBB0_126
	s_and_b64 vcc, exec, s[48:49]
	s_cbranch_vccz .LBB0_122

; __device__ __forceinline__ unsigned xb_ld(unsigned* p)              { return __hip_atomic_load(p, __ATOMIC_RELAXED, __HIP_MEMORY_SCOPE_AGENT); }
; __device__ __forceinline__ void xcd_barrier_complete(unsigned* bar, unsigned x, unsigned& nloc, unsigned& nx) {
;     ...
;     for (;;) {
;         sum = 0u; cnt = 0u; mine = 0u;
; #pragma unroll
;         for (unsigned j = 0; j < 16; ++j) { const unsigned c = xb_ld(&bar[XB_XCNT(j)]); sum += c; cnt += (c > 0u) ? 1u : 0u; mine = (j == x) ? c : mine; }
;         if (sum == G) break;
;         __builtin_amdgcn_s_sleep(1);
;         if ((++sp & 255u) == 0u) { if (xb_ld(&bar[XB_TMO])) break; if (sp > XB_SPIN_CAP) { atomicAdd(&bar[XB_TMO], 1u); break; } }
;     }
.LBB0_665:
	v_readlane_b32 s8, v251, 45
	v_readlane_b32 s9, v251, 46
	global_load_dword v12, v1, s[18:19] offset:1024 sc1
	global_load_dword v0, v1, s[18:19] offset:1280 sc1
	s_waitcnt lgkmcnt(0)
	global_load_dword v2, v1, s[18:19] offset:1536 sc1
	global_load_dword v3, v1, s[18:19] offset:1792 sc1
	global_load_dword v4, v1, s[18:19] offset:2048 sc1
	global_load_dword v5, v1, s[18:19] offset:2304 sc1
	global_load_dword v6, v1, s[18:19] offset:2560 sc1
	global_load_dword v7, v1, s[18:19] offset:2816 sc1
	global_load_dword v8, v1, s[18:19] offset:3072 sc1
	global_load_dword v9, v1, s[18:19] offset:3328 sc1
	global_load_dword v10, v1, s[18:19] offset:3584 sc1
	global_load_dword v11, v1, s[18:19] offset:3840 sc1
	global_load_dword v13, v1, s[8:9] sc1
	v_readlane_b32 s8, v251, 47
	v_readlane_b32 s9, v251, 48
	s_mov_b64 s[20:21], -1
	s_mov_b64 s[38:39], -1
	s_waitcnt vmcnt(11)
	v_add_u32_e32 v17, v0, v12
	s_nop 0
	global_load_dword v14, v1, s[8:9] sc1
	v_readlane_b32 s8, v251, 49
	v_readlane_b32 s9, v251, 50
	s_waitcnt vmcnt(11)
	v_add_u32_e32 v17, v17, v2
	s_waitcnt vmcnt(10)
	v_add_u32_e32 v17, v17, v3
	s_waitcnt vmcnt(9)
	v_add_u32_e32 v17, v17, v4
	s_waitcnt vmcnt(8)
	v_add_u32_e32 v17, v17, v5
	s_waitcnt vmcnt(7)
	v_add_u32_e32 v17, v17, v6
	global_load_dword v15, v1, s[8:9] sc1
	v_readlane_b32 s8, v251, 51
	v_readlane_b32 s9, v251, 52
	s_waitcnt vmcnt(7)
	v_add_u32_e32 v17, v17, v7
	s_waitcnt vmcnt(6)
	v_add_u32_e32 v17, v17, v8
	s_waitcnt vmcnt(5)
	v_add_u32_e32 v17, v17, v9
	s_waitcnt vmcnt(4)
	v_add_u32_e32 v17, v17, v10
	s_waitcnt vmcnt(3)
	v_add_u32_e32 v17, v17, v11
	global_load_dword v16, v1, s[8:9] sc1
	s_waitcnt vmcnt(3)
	v_add_u32_e32 v17, v17, v13
	v_readlane_b32 s8, v254, 29
	s_waitcnt vmcnt(2)
	v_add_u32_e32 v17, v17, v14
	s_waitcnt vmcnt(1)
	v_add_u32_e32 v17, v17, v15
	s_waitcnt vmcnt(0)
	v_add_u32_e32 v17, v17, v16
	v_cmp_eq_u32_e32 vcc, s8, v17
	s_cbranch_vccnz .LBB0_664
	s_and_b32 s8, s4, 0xff
	s_cmp_eq_u32 s8, 0
	s_mov_b64 s[40:41], -1
	s_sleep 4
	s_cbranch_scc1 .LBB0_669
	s_and_b64 vcc, exec, s[40:41]
	s_cbranch_vccz .LBB0_664

.LBB0_829:
	s_and_b32 s8, s4, 0xff
	s_mov_b64 s[46:47], -1
	s_cmp_lg_u32 s8, 0
	s_mov_b64 s[50:51], -1
	s_sleep 4
	s_cbranch_scc0 .LBB0_832
	s_and_b64 vcc, exec, s[50:51]
	s_cbranch_vccz .LBB0_828
